# P0b input-norm phase: per-round reloads of norm gain and adaLN scale/shift quarters (3 loads + vmcnt drain x15 per iteration) replaced by one load per distinct quarter per iteration
# speedup vs baseline: 1.0056x; 1.0056x over previous
.LBB0_138:
	v_lshl_add_u64 v[2:3], s[36:37], 0, v[204:205]
	v_lshl_add_u64 v[4:5], s[70:71], 0, v[204:205]
	v_lshl_add_u64 v[10:11], s[62:63], 0, v[204:205]
	v_lshl_add_u64 v[70:71], s[56:57], 0, v[204:205]
	global_load_dwordx4 v[6:9], v[74:75], off
	global_load_dwordx4 v[66:69], v[2:3], off
	global_load_dwordx4 v[58:61], v[2:3], off offset:1024
	global_load_dwordx4 v[54:57], v[2:3], off offset:3072
	global_load_dwordx4 v[62:65], v[2:3], off offset:2048
	global_load_dwordx4 v[50:53], v[4:5], off
	global_load_dwordx4 v[42:45], v[4:5], off offset:1024
	global_load_dwordx4 v[38:41], v[4:5], off offset:3072
	global_load_dwordx4 v[46:49], v[4:5], off offset:2048
	global_load_dwordx4 v[34:37], v[10:11], off
	global_load_dwordx4 v[30:33], v[10:11], off offset:1024
	global_load_dwordx4 v[26:29], v[10:11], off offset:2048
	global_load_dwordx4 v[22:25], v[10:11], off offset:3072
	global_load_dwordx4 v[18:21], v[70:71], off
	global_load_dwordx4 v[14:17], v[70:71], off offset:1024
	s_nop 0
	global_load_dwordx4 v[10:13], v[70:71], off offset:2048
	global_load_dwordx4 v[2:5], v[70:71], off offset:3072
	s_ashr_i32 s0, s38, 13
	v_lshl_add_u64 v[72:73], s[60:61], 0, v[200:201]
	v_lshl_add_u64 v[76:77], s[68:69], 0, v[200:201]
	s_mul_i32 s8, s0, 0x1800
	v_add_co_u32_e32 v82, vcc, s33, v72
	v_add_co_u32_e64 v80, s[0:1], s33, v76
	s_ashr_i32 s9, s8, 31
	v_addc_co_u32_e32 v83, vcc, 0, v73, vcc
	v_addc_co_u32_e64 v81, vcc, 0, v77, s[0:1]
	s_lshl_b64 s[0:1], s[8:9], 2
	s_add_u32 s78, s28, s0
	s_addc_u32 s79, s29, s1
	v_lshl_add_u64 v[96:97], s[30:31], 0, v[200:201]
	s_add_u32 s80, s78, 0x1000
	v_add_co_u32_e64 v76, s[6:7], s33, v96
	s_addc_u32 s81, s79, 0
	s_nop 0
	v_addc_co_u32_e64 v77, vcc, 0, v97, s[6:7]
	global_load_dwordx4 v[70:73], v92, s[78:79]
	global_load_dwordx4 v[96:99], v92, s[80:81]
	s_add_i32 s0, s38, 0x800
	s_ashr_i32 s0, s0, 13
	s_mulk_i32 s0, 0x1800
	s_ashr_i32 s1, s0, 31
	s_lshl_b64 s[0:1], s[0:1], 2
	s_add_u32 s54, s28, s0
	s_addc_u32 s55, s29, s1
	s_add_u32 s74, s54, 0x1000
	s_addc_u32 s75, s55, 0
	s_add_i32 s0, s38, 0x1000
	s_ashr_i32 s0, s0, 13
	s_mulk_i32 s0, 0x1800
	s_ashr_i32 s1, s0, 31
	s_lshl_b64 s[0:1], s[0:1], 2
	s_add_u32 s66, s28, s0
	s_addc_u32 s67, s29, s1
	s_add_u32 s72, s66, 0x1000
	s_addc_u32 s73, s67, 0
	s_add_i32 s0, s38, 0x1800
	v_lshl_add_u64 v[78:79], s[58:59], 0, v[200:201]
	s_ashr_i32 s0, s0, 13
	v_add_co_u32_e64 v78, s[4:5], s33, v78
	s_mulk_i32 s0, 0x1800
	s_nop 0
	v_addc_co_u32_e64 v79, vcc, 0, v79, s[4:5]
	s_ashr_i32 s1, s0, 31
	s_lshl_b64 s[0:1], s[0:1], 2
	s_add_u32 s52, s28, s0
	s_addc_u32 s53, s29, s1
	s_add_u32 s64, s52, 0x1000
	s_addc_u32 s65, s53, 0
	s_add_u32 s30, s30, 0x1000000
	s_addc_u32 s31, s31, 0
	s_add_u32 s36, s36, 0x2000000
	s_addc_u32 s37, s37, 0
	s_add_u32 s56, s56, 0x2000000
	s_addc_u32 s57, s57, 0
	s_add_u32 s58, s58, 0x1000000
	s_waitcnt vmcnt(17)
	v_pk_mul_f32 v[100:101], v[68:69], v[68:69]
	v_pk_mul_f32 v[102:103], v[66:67], v[66:67]
	s_waitcnt vmcnt(16)
	v_pk_mul_f32 v[104:105], v[60:61], v[60:61]
	v_pk_mul_f32 v[106:107], v[58:59], v[58:59]
	s_waitcnt vmcnt(13)
	v_pk_mul_f32 v[112:113], v[52:53], v[52:53]
	v_pk_mul_f32 v[114:115], v[50:51], v[50:51]
	s_waitcnt vmcnt(12)
	v_pk_mul_f32 v[116:117], v[44:45], v[44:45]
	v_pk_mul_f32 v[118:119], v[42:43], v[42:43]
	v_mul_f32_e32 v109, v56, v56
	v_mul_f32_e32 v108, v63, v63
	v_mul_f32_e32 v110, v65, v65
	s_waitcnt vmcnt(10)
	v_mul_f32_e32 v120, v47, v47
	v_mul_f32_e32 v122, v49, v49
	s_waitcnt vmcnt(9)
	v_pk_mul_f32 v[124:125], v[36:37], v[36:37]
	v_pk_mul_f32 v[126:127], v[34:35], v[34:35]
	s_waitcnt vmcnt(8)
	v_pk_mul_f32 v[128:129], v[32:33], v[32:33]
	v_pk_mul_f32 v[130:131], v[30:31], v[30:31]
	v_pk_mov_b32 v[140:141], v[102:103], v[100:101] op_sel:[1,0]
	v_mov_b32_e32 v103, v101
	v_pk_mov_b32 v[100:101], v[106:107], v[104:105] op_sel:[1,0]
	v_mov_b32_e32 v107, v105
	v_pk_mov_b32 v[104:105], v[114:115], v[112:113] op_sel:[1,0]
	v_mov_b32_e32 v115, v113
	v_pk_mov_b32 v[112:113], v[118:119], v[116:117] op_sel:[1,0]
	v_mov_b32_e32 v119, v117
	v_mul_f32_e32 v144, v57, v57
	v_mul_f32_e32 v147, v40, v40
	v_mul_f32_e32 v149, v41, v41
	s_waitcnt vmcnt(5)
	v_pk_mul_f32 v[132:133], v[20:21], v[20:21]
	v_pk_mul_f32 v[134:135], v[18:19], v[18:19]
	s_waitcnt vmcnt(4)
	v_pk_mul_f32 v[136:137], v[16:17], v[16:17]
	v_pk_mul_f32 v[138:139], v[14:15], v[14:15]
	v_pk_mov_b32 v[116:117], v[126:127], v[124:125] op_sel:[1,0]
	v_mov_b32_e32 v127, v125
	v_pk_mov_b32 v[124:125], v[130:131], v[128:129] op_sel:[1,0]
	v_mov_b32_e32 v131, v129
	v_pk_add_f32 v[102:103], v[140:141], v[102:103]
	v_pk_add_f32 v[100:101], v[100:101], v[106:107]
	v_pk_fma_f32 v[106:107], v[62:63], v[62:63], v[108:109] op_sel_hi:[1,1,0]
	v_pk_add_f32 v[112:113], v[112:113], v[118:119]
	v_pk_fma_f32 v[110:111], v[64:65], v[64:65], v[110:111] op_sel_hi:[1,1,0]
	v_pk_fma_f32 v[118:119], v[46:47], v[46:47], v[120:121] op_sel_hi:[1,1,0]
	v_pk_fma_f32 v[120:121], v[48:49], v[48:49], v[122:123] op_sel_hi:[1,1,0]
	v_mul_f32_e32 v142, v54, v54
	v_mul_f32_e32 v143, v55, v55
	v_pk_mov_b32 v[128:129], v[134:135], v[132:133] op_sel:[1,0]
	v_mov_b32_e32 v135, v133
	v_pk_mov_b32 v[132:133], v[138:139], v[136:137] op_sel:[1,0]
	v_mul_f32_e32 v136, v27, v27
	v_mul_f32_e32 v140, v29, v29
	s_waitcnt vmcnt(2)
	global_load_dwordx4 v[158:161], v[74:75], off
	global_load_dwordx4 v[174:177], v92, s[80:81]
	global_load_dwordx4 v[190:193], v92, s[78:79]
	global_load_dwordx4 v[162:165], v[74:75], off offset:1024
	global_load_dwordx4 v[178:181], v93, s[80:81]
	global_load_dwordx4 v[194:197], v92, s[78:79] offset:1024
	global_load_dwordx4 v[166:169], v[74:75], off offset:2048
	global_load_dwordx4 v[182:185], v94, s[80:81]
	global_load_dwordx4 v[206:209], v92, s[78:79] offset:2048
	global_load_dwordx4 v[170:173], v[74:75], off offset:3072
	global_load_dwordx4 v[186:189], v95, s[80:81]
	global_load_dwordx4 v[210:213], v92, s[78:79] offset:3072
	v_mul_f32_e32 v141, v2, v2
	v_mov_b32_e32 v107, v109
	v_pk_add_f32 v[104:105], v[104:105], v[114:115]
	v_mov_b32_e32 v111, v144
	v_mov_b32_e32 v119, v147
	v_mov_b32_e32 v121, v149
	v_pk_add_f32 v[116:117], v[116:117], v[126:127]
	v_pk_add_f32 v[124:125], v[124:125], v[130:131]
	v_pk_add_f32 v[102:103], v[102:103], v[102:103] op_sel:[0,1] op_sel_hi:[1,0]
	v_pk_add_f32 v[100:101], v[100:101], v[100:101] op_sel:[0,1] op_sel_hi:[1,0]
	v_mul_f32_e32 v145, v38, v38
	v_mul_f32_e32 v146, v39, v39
	v_mul_f32_e32 v150, v22, v22
	v_mul_f32_e32 v151, v23, v23
	v_mul_f32_e32 v152, v24, v24
	v_mul_f32_e32 v153, v25, v25
	v_mov_b32_e32 v139, v137
	v_pk_fma_f32 v[122:123], v[26:27], v[26:27], v[136:137] op_sel_hi:[1,1,0]
	v_pk_fma_f32 v[136:137], v[28:29], v[28:29], v[140:141] op_sel_hi:[1,1,0]
	v_pk_add_f32 v[106:107], v[106:107], v[110:111]
	v_pk_add_f32 v[104:105], v[104:105], v[104:105] op_sel:[0,1] op_sel_hi:[1,0]
	v_pk_add_f32 v[110:111], v[112:113], v[112:113] op_sel:[0,1] op_sel_hi:[1,0]
	v_pk_add_f32 v[112:113], v[118:119], v[120:121]
	v_pk_add_f32 v[116:117], v[116:117], v[116:117] op_sel:[0,1] op_sel_hi:[1,0]
	v_pk_add_f32 v[118:119], v[124:125], v[124:125] op_sel:[0,1] op_sel_hi:[1,0]
	v_mov_b32_e32 v103, v142
	v_mov_b32_e32 v101, v143
	v_mov_b32_e32 v123, v152
	v_mov_b32_e32 v137, v153
	v_mov_b32_e32 v105, v145
	v_mov_b32_e32 v111, v146
	v_mov_b32_e32 v117, v150
	v_mov_b32_e32 v119, v151
	v_pk_add_f32 v[100:101], v[102:103], v[100:101]
	v_mul_f32_e32 v108, v11, v11
	v_mul_f32_e32 v114, v13, v13
	v_pk_add_f32 v[126:127], v[128:129], v[134:135]
	v_pk_add_f32 v[128:129], v[132:133], v[138:139]
	v_pk_add_f32 v[120:121], v[122:123], v[136:137]
	v_pk_add_f32 v[102:103], v[104:105], v[110:111]
	v_pk_add_f32 v[104:105], v[116:117], v[118:119]
	v_pk_add_f32 v[100:101], v[100:101], v[106:107]
	v_mul_f32_e32 v154, v3, v3
	v_mul_f32_e32 v155, v4, v4
	v_mul_f32_e32 v156, v5, v5
	v_pk_fma_f32 v[108:109], v[10:11], v[10:11], v[108:109] op_sel_hi:[1,1,0]
	v_pk_fma_f32 v[114:115], v[12:13], v[12:13], v[114:115] op_sel_hi:[1,1,0]
	v_pk_add_f32 v[122:123], v[126:127], v[126:127] op_sel:[0,1] op_sel_hi:[1,0]
	v_pk_add_f32 v[124:125], v[128:129], v[128:129] op_sel:[0,1] op_sel_hi:[1,0]
	v_pk_add_f32 v[102:103], v[102:103], v[112:113]
	v_pk_add_f32 v[104:105], v[104:105], v[120:121]
	v_add_f32_e32 v100, v100, v101
	v_mov_b32_e32 v109, v155
	v_mov_b32_e32 v115, v156
	v_mov_b32_e32 v123, v141
	v_mov_b32_e32 v125, v154
	v_add_f32_e32 v101, v102, v103
	v_add_f32_e32 v102, v104, v105
	ds_bpermute_b32 v104, v84, v100
	v_pk_add_f32 v[108:109], v[108:109], v[114:115]
	v_pk_add_f32 v[110:111], v[122:123], v[124:125]
	ds_bpermute_b32 v105, v84, v101
	v_pk_add_f32 v[106:107], v[110:111], v[108:109]
	s_waitcnt lgkmcnt(1)
	v_add_f32_e32 v100, v100, v104
	v_add_f32_e32 v103, v106, v107
	ds_bpermute_b32 v106, v84, v102
	ds_bpermute_b32 v104, v85, v100
	s_waitcnt lgkmcnt(2)
	v_add_f32_e32 v101, v101, v105
	ds_bpermute_b32 v105, v85, v101
	ds_bpermute_b32 v107, v84, v103
	s_waitcnt lgkmcnt(3)
	v_add_f32_e32 v102, v102, v106
	ds_bpermute_b32 v106, v85, v102
	s_waitcnt lgkmcnt(3)
	v_add_f32_e32 v100, v100, v104
	ds_bpermute_b32 v104, v86, v100
	s_waitcnt lgkmcnt(3)
	v_add_f32_e32 v101, v101, v105
	ds_bpermute_b32 v105, v86, v101
	s_waitcnt lgkmcnt(2)
	v_add_f32_e32 v102, v102, v106
	ds_bpermute_b32 v106, v86, v102
	s_waitcnt lgkmcnt(2)
	v_add_f32_e32 v100, v100, v104
	ds_bpermute_b32 v104, v87, v100
	s_waitcnt lgkmcnt(2)
	v_add_f32_e32 v101, v101, v105
	ds_bpermute_b32 v105, v87, v101
	s_waitcnt lgkmcnt(2)
	v_add_f32_e32 v102, v102, v106
	ds_bpermute_b32 v106, v87, v102
	s_waitcnt lgkmcnt(2)
	v_add_f32_e32 v100, v100, v104
	ds_bpermute_b32 v104, v88, v100
	s_waitcnt lgkmcnt(2)
	v_add_f32_e32 v101, v101, v105
	ds_bpermute_b32 v105, v88, v101
	s_waitcnt lgkmcnt(2)
	v_add_f32_e32 v102, v102, v106
	ds_bpermute_b32 v106, v88, v102
	s_waitcnt lgkmcnt(2)
	v_add_f32_e32 v100, v100, v104
	ds_bpermute_b32 v104, v89, v100
	v_add_f32_e32 v103, v103, v107
	s_waitcnt lgkmcnt(2)
	v_add_f32_e32 v101, v101, v105
	ds_bpermute_b32 v107, v85, v103
	s_waitcnt lgkmcnt(2)
	v_add_f32_e32 v102, v102, v106
	ds_bpermute_b32 v105, v89, v101
	ds_bpermute_b32 v106, v89, v102
	s_waitcnt lgkmcnt(3)
	v_add_f32_e32 v100, v100, v104
	v_fmamk_f32 v100, v100, 0x3a800000, v90
	s_waitcnt lgkmcnt(2)
	v_add_f32_e32 v103, v103, v107
	s_waitcnt lgkmcnt(1)
	v_add_f32_e32 v101, v101, v105
	v_cmp_gt_f32_e32 vcc, s3, v100
	v_mul_f32_e32 v104, 0x4f800000, v100
	ds_bpermute_b32 v107, v86, v103
	s_waitcnt lgkmcnt(1)
	v_add_f32_e32 v102, v102, v106
	v_fmamk_f32 v101, v101, 0x3a800000, v90
	v_cndmask_b32_e32 v100, v100, v104, vcc
	v_fmamk_f32 v102, v102, 0x3a800000, v90
	v_cmp_gt_f32_e64 s[0:1], s3, v101
	v_mul_f32_e32 v105, 0x4f800000, v101
	v_sqrt_f32_e32 v104, v100
	v_cmp_gt_f32_e64 s[4:5], s3, v102
	v_mul_f32_e32 v106, 0x4f800000, v102
	v_cndmask_b32_e64 v101, v101, v105, s[0:1]
	v_cndmask_b32_e64 v102, v102, v106, s[4:5]
	v_sqrt_f32_e32 v105, v101
	v_sqrt_f32_e32 v106, v102
	s_waitcnt lgkmcnt(0)
	v_add_f32_e32 v103, v103, v107
	v_add_u32_e32 v107, -1, v104
	v_add_u32_e32 v108, 1, v104
	v_fma_f32 v113, -v107, v104, v100
	v_add_u32_e32 v109, -1, v105
	v_fma_f32 v114, -v108, v104, v100
	v_cmp_ge_f32_e64 s[12:13], 0, v113
	v_add_u32_e32 v110, 1, v105
	v_add_u32_e32 v111, -1, v106
	v_fma_f32 v115, -v109, v105, v101
	v_cmp_lt_f32_e64 s[16:17], 0, v114
	v_cndmask_b32_e64 v104, v104, v107, s[12:13]
	v_add_u32_e32 v112, 1, v106
	v_fma_f32 v116, -v110, v105, v101
	v_fma_f32 v117, -v111, v106, v102
	v_cmp_ge_f32_e64 s[18:19], 0, v115
	v_cndmask_b32_e64 v104, v104, v108, s[16:17]
	v_fma_f32 v118, -v112, v106, v102
	v_cmp_lt_f32_e64 s[20:21], 0, v116
	v_cmp_ge_f32_e64 s[22:23], 0, v117
	v_cndmask_b32_e64 v105, v105, v109, s[18:19]
	v_mul_f32_e32 v107, 0x37800000, v104
	v_cmp_class_f32_e64 s[6:7], v100, v91
	v_cmp_lt_f32_e64 s[24:25], 0, v118
	v_cndmask_b32_e64 v106, v106, v111, s[22:23]
	v_cndmask_b32_e64 v105, v105, v110, s[20:21]
	v_cndmask_b32_e32 v104, v104, v107, vcc
	v_cndmask_b32_e64 v106, v106, v112, s[24:25]
	v_mul_f32_e32 v108, 0x37800000, v105
	v_cndmask_b32_e64 v100, v104, v100, s[6:7]
	v_cmp_class_f32_e64 s[8:9], v101, v91
	v_mul_f32_e32 v109, 0x37800000, v106
	v_cndmask_b32_e64 v105, v105, v108, s[0:1]
	v_div_scale_f32 v104, s[0:1], v100, v100, 1.0
	v_cmp_class_f32_e64 s[10:11], v102, v91
	v_cndmask_b32_e64 v106, v106, v109, s[4:5]
	v_cndmask_b32_e64 v101, v105, v101, s[8:9]
	v_rcp_f32_e32 v110, v104
	v_cndmask_b32_e64 v102, v106, v102, s[10:11]
	v_div_scale_f32 v106, s[0:1], v101, v101, 1.0
	v_div_scale_f32 v108, s[4:5], v102, v102, 1.0
	v_rcp_f32_e32 v111, v106
	v_rcp_f32_e32 v112, v108
	v_fma_f32 v113, -v104, v110, 1.0
	v_div_scale_f32 v105, vcc, 1.0, v100, 1.0
	v_fmac_f32_e32 v110, v113, v110
	v_fma_f32 v114, -v106, v111, 1.0
	v_mul_f32_e32 v113, v105, v110
	v_div_scale_f32 v107, s[0:1], 1.0, v101, 1.0
	v_fma_f32 v115, -v108, v112, 1.0
	v_fmac_f32_e32 v111, v114, v111
	v_fma_f32 v116, -v104, v113, v105
	v_div_scale_f32 v109, s[4:5], 1.0, v102, 1.0
	v_fmac_f32_e32 v112, v115, v112
	v_mul_f32_e32 v114, v107, v111
	v_fmac_f32_e32 v113, v116, v110
	v_mul_f32_e32 v115, v109, v112
	v_fma_f32 v117, -v106, v114, v107
	v_fma_f32 v104, -v104, v113, v105
	v_fma_f32 v118, -v108, v115, v109
	v_fmac_f32_e32 v114, v117, v111
	v_div_fmas_f32 v104, v104, v110, v113
	v_fmac_f32_e32 v115, v118, v112
	v_fma_f32 v105, -v106, v114, v107
	v_div_fixup_f32 v100, v104, v100, 1.0
	s_mov_b64 vcc, s[0:1]
	v_fma_f32 v106, -v108, v115, v109
	v_div_fmas_f32 v104, v105, v111, v114
	v_pk_mul_f32 v[68:69], v[68:69], v[100:101] op_sel_hi:[1,0]
	v_pk_mul_f32 v[66:67], v[66:67], v[100:101] op_sel_hi:[1,0]
	s_mov_b64 vcc, s[4:5]
	s_waitcnt vmcnt(0)
	v_pk_add_f32 v[98:99], v[98:99], 1.0 op_sel_hi:[1,0]
	v_pk_add_f32 v[96:97], v[96:97], 1.0 op_sel_hi:[1,0]
	v_pk_mul_f32 v[60:61], v[60:61], v[100:101] op_sel_hi:[1,0]
	v_pk_mul_f32 v[58:59], v[58:59], v[100:101] op_sel_hi:[1,0]
	v_pk_mul_f32 v[64:65], v[64:65], v[100:101] op_sel_hi:[1,0]
	v_pk_mul_f32 v[62:63], v[62:63], v[100:101] op_sel_hi:[1,0]
	v_pk_mul_f32 v[56:57], v[56:57], v[100:101] op_sel_hi:[1,0]
	v_pk_mul_f32 v[54:55], v[54:55], v[100:101] op_sel_hi:[1,0]
	v_div_fixup_f32 v100, v104, v101, 1.0
	v_div_fmas_f32 v104, v106, v112, v115
	v_pk_mul_f32 v[66:67], v[6:7], v[66:67]
	v_pk_mul_f32 v[8:9], v[8:9], v[68:69]
	v_pk_mul_f32 v[52:53], v[52:53], v[100:101] op_sel_hi:[1,0]
	v_pk_mul_f32 v[50:51], v[50:51], v[100:101] op_sel_hi:[1,0]
	v_pk_mul_f32 v[44:45], v[44:45], v[100:101] op_sel_hi:[1,0]
	v_pk_mul_f32 v[42:43], v[42:43], v[100:101] op_sel_hi:[1,0]
	v_pk_mul_f32 v[48:49], v[48:49], v[100:101] op_sel_hi:[1,0]
	v_pk_mul_f32 v[46:47], v[46:47], v[100:101] op_sel_hi:[1,0]
	v_pk_mul_f32 v[68:69], v[40:41], v[100:101] op_sel_hi:[1,0]
	v_pk_mul_f32 v[100:101], v[38:39], v[100:101] op_sel_hi:[1,0]
	v_div_fixup_f32 v6, v104, v102, 1.0
	v_pk_fma_f32 v[8:9], v[98:99], v[8:9], v[72:73]
	v_pk_fma_f32 v[38:39], v[96:97], v[66:67], v[70:71]
	v_pk_mul_f32 v[66:67], v[36:37], v[6:7] op_sel_hi:[1,0]
	v_pk_mul_f32 v[70:71], v[34:35], v[6:7] op_sel_hi:[1,0]
	v_pk_mul_f32 v[72:73], v[32:33], v[6:7] op_sel_hi:[1,0]
	v_pk_mul_f32 v[96:97], v[30:31], v[6:7] op_sel_hi:[1,0]
	v_bfe_u32 v7, v38, 16, 1
	v_bfe_u32 v31, v8, 16, 1
	v_bfe_u32 v30, v39, 16, 1
	v_bfe_u32 v32, v9, 16, 1
	v_add3_u32 v7, v38, v7, s26
	v_add3_u32 v8, v8, v31, s26
	v_add3_u32 v30, v39, v30, s26
	v_add3_u32 v9, v9, v32, s26
	v_lshrrev_b32_e32 v7, 16, v7
	v_lshrrev_b32_e32 v31, 16, v8
	v_and_or_b32 v8, v30, s27, v7
	v_and_or_b32 v9, v9, s27, v31
	global_store_dwordx2 v[82:83], v[8:9], off
	s_addc_u32 s59, s59, 0
	s_add_u32 s60, s60, 0x1000000
	s_addc_u32 s61, s61, 0
	s_add_u32 s62, s62, 0x2000000
	s_addc_u32 s63, s63, 0
	s_add_u32 s68, s68, 0x1000000
	s_addc_u32 s69, s69, 0
	s_add_u32 s70, s70, 0x2000000
	s_addc_u32 s71, s71, 0
	v_pk_mul_f32 v[8:9], v[162:163], v[58:59]
	v_pk_mul_f32 v[30:31], v[164:165], v[60:61]
	v_pk_add_f32 v[32:33], v[180:181], 1.0 op_sel_hi:[1,0]
	v_pk_add_f32 v[34:35], v[178:179], 1.0 op_sel_hi:[1,0]
	v_pk_fma_f32 v[30:31], v[32:33], v[30:31], v[196:197]
	v_pk_fma_f32 v[8:9], v[34:35], v[8:9], v[194:195]
	v_bfe_u32 v33, v30, 16, 1
	v_bfe_u32 v7, v8, 16, 1
	v_bfe_u32 v32, v9, 16, 1
	v_bfe_u32 v34, v31, 16, 1
	v_add3_u32 v7, v8, v7, s26
	v_add3_u32 v8, v9, v32, s26
	v_add3_u32 v9, v30, v33, s26
	v_add3_u32 v30, v31, v34, s26
	v_lshrrev_b32_e32 v7, 16, v7
	v_lshrrev_b32_e32 v9, 16, v9
	v_and_or_b32 v8, v8, s27, v7
	v_and_or_b32 v9, v30, s27, v9
	global_store_dwordx2 v[82:83], v[8:9], off offset:512
	v_pk_mul_f32 v[8:9], v[166:167], v[62:63]
	v_pk_mul_f32 v[30:31], v[168:169], v[64:65]
	v_pk_add_f32 v[32:33], v[184:185], 1.0 op_sel_hi:[1,0]
	v_pk_add_f32 v[34:35], v[182:183], 1.0 op_sel_hi:[1,0]
	v_pk_fma_f32 v[30:31], v[30:31], v[32:33], v[208:209]
	v_pk_fma_f32 v[8:9], v[8:9], v[34:35], v[206:207]
	v_bfe_u32 v33, v30, 16, 1
	v_bfe_u32 v7, v8, 16, 1
	v_bfe_u32 v32, v9, 16, 1
	v_bfe_u32 v34, v31, 16, 1
	v_add3_u32 v7, v8, v7, s26
	v_add3_u32 v8, v9, v32, s26
	v_add3_u32 v9, v30, v33, s26
	v_add3_u32 v30, v31, v34, s26
	v_lshrrev_b32_e32 v7, 16, v7
	v_lshrrev_b32_e32 v9, 16, v9
	v_and_or_b32 v8, v8, s27, v7
	v_and_or_b32 v9, v30, s27, v9
	global_store_dwordx2 v[82:83], v[8:9], off offset:1024
	v_pk_mul_f32 v[8:9], v[54:55], v[170:171]
	v_pk_mul_f32 v[30:31], v[56:57], v[172:173]
	v_pk_add_f32 v[32:33], v[188:189], 1.0 op_sel_hi:[1,0]
	v_pk_add_f32 v[34:35], v[186:187], 1.0 op_sel_hi:[1,0]
	v_pk_fma_f32 v[30:31], v[30:31], v[32:33], v[212:213]
	v_pk_fma_f32 v[8:9], v[8:9], v[34:35], v[210:211]
	v_bfe_u32 v33, v30, 16, 1
	v_bfe_u32 v7, v8, 16, 1
	v_bfe_u32 v32, v9, 16, 1
	v_bfe_u32 v34, v31, 16, 1
	v_add3_u32 v7, v8, v7, s26
	v_add3_u32 v8, v9, v32, s26
	v_add3_u32 v9, v30, v33, s26
	v_add3_u32 v30, v31, v34, s26
	v_lshrrev_b32_e32 v7, 16, v7
	v_lshrrev_b32_e32 v9, 16, v9
	v_and_or_b32 v8, v8, s27, v7
	v_and_or_b32 v9, v30, s27, v9
	global_store_dwordx2 v[82:83], v[8:9], off offset:1536
	v_pk_mul_f32 v[8:9], v[158:159], v[50:51]
	v_pk_mul_f32 v[30:31], v[160:161], v[52:53]
	v_pk_add_f32 v[32:33], v[176:177], 1.0 op_sel_hi:[1,0]
	v_pk_add_f32 v[34:35], v[174:175], 1.0 op_sel_hi:[1,0]
	v_pk_fma_f32 v[30:31], v[32:33], v[30:31], v[192:193]
	v_pk_fma_f32 v[8:9], v[34:35], v[8:9], v[190:191]
	v_bfe_u32 v33, v30, 16, 1
	v_bfe_u32 v7, v8, 16, 1
	v_bfe_u32 v32, v9, 16, 1
	v_bfe_u32 v34, v31, 16, 1
	v_add3_u32 v7, v8, v7, s26
	v_add3_u32 v8, v9, v32, s26
	v_add3_u32 v9, v30, v33, s26
	v_add3_u32 v30, v31, v34, s26
	v_lshrrev_b32_e32 v7, 16, v7
	v_lshrrev_b32_e32 v9, 16, v9
	v_and_or_b32 v8, v8, s27, v7
	v_and_or_b32 v9, v30, s27, v9
	global_store_dwordx2 v[80:81], v[8:9], off
	v_pk_mul_f32 v[8:9], v[162:163], v[42:43]
	v_pk_mul_f32 v[30:31], v[164:165], v[44:45]
	v_pk_add_f32 v[32:33], v[180:181], 1.0 op_sel_hi:[1,0]
	v_pk_add_f32 v[34:35], v[178:179], 1.0 op_sel_hi:[1,0]
	v_pk_fma_f32 v[30:31], v[32:33], v[30:31], v[196:197]
	v_pk_fma_f32 v[8:9], v[34:35], v[8:9], v[194:195]
	v_bfe_u32 v33, v30, 16, 1
	v_bfe_u32 v7, v8, 16, 1
	v_bfe_u32 v32, v9, 16, 1
	v_bfe_u32 v34, v31, 16, 1
	v_add3_u32 v7, v8, v7, s26
	v_add3_u32 v8, v9, v32, s26
	v_add3_u32 v9, v30, v33, s26
	v_add3_u32 v30, v31, v34, s26
	v_lshrrev_b32_e32 v7, 16, v7
	v_lshrrev_b32_e32 v9, 16, v9
	v_and_or_b32 v8, v8, s27, v7
	v_and_or_b32 v9, v30, s27, v9
	global_store_dwordx2 v[80:81], v[8:9], off offset:512
	v_pk_mul_f32 v[8:9], v[166:167], v[46:47]
	v_pk_mul_f32 v[30:31], v[168:169], v[48:49]
	v_pk_add_f32 v[32:33], v[184:185], 1.0 op_sel_hi:[1,0]
	v_pk_add_f32 v[34:35], v[182:183], 1.0 op_sel_hi:[1,0]
	v_pk_fma_f32 v[30:31], v[30:31], v[32:33], v[208:209]
	v_pk_fma_f32 v[8:9], v[8:9], v[34:35], v[206:207]
	v_bfe_u32 v33, v30, 16, 1
	v_bfe_u32 v7, v8, 16, 1
	v_bfe_u32 v32, v9, 16, 1
	v_bfe_u32 v34, v31, 16, 1
	v_add3_u32 v7, v8, v7, s26
	v_add3_u32 v8, v9, v32, s26
	v_add3_u32 v9, v30, v33, s26
	v_add3_u32 v30, v31, v34, s26
	v_lshrrev_b32_e32 v7, 16, v7
	v_lshrrev_b32_e32 v9, 16, v9
	v_and_or_b32 v8, v8, s27, v7
	v_and_or_b32 v9, v30, s27, v9
	global_store_dwordx2 v[80:81], v[8:9], off offset:1024
	v_pk_mul_f32 v[8:9], v[100:101], v[170:171]
	v_pk_mul_f32 v[30:31], v[68:69], v[172:173]
	v_pk_add_f32 v[32:33], v[188:189], 1.0 op_sel_hi:[1,0]
	v_pk_add_f32 v[34:35], v[186:187], 1.0 op_sel_hi:[1,0]
	v_pk_fma_f32 v[30:31], v[30:31], v[32:33], v[212:213]
	v_pk_fma_f32 v[8:9], v[8:9], v[34:35], v[210:211]
	v_bfe_u32 v33, v30, 16, 1
	v_bfe_u32 v7, v8, 16, 1
	v_bfe_u32 v32, v9, 16, 1
	v_bfe_u32 v34, v31, 16, 1
	v_add3_u32 v7, v8, v7, s26
	v_add3_u32 v8, v9, v32, s26
	v_add3_u32 v9, v30, v33, s26
	v_add3_u32 v30, v31, v34, s26
	v_lshrrev_b32_e32 v7, 16, v7
	v_lshrrev_b32_e32 v9, 16, v9
	v_and_or_b32 v8, v8, s27, v7
	v_and_or_b32 v9, v30, s27, v9
	global_store_dwordx2 v[80:81], v[8:9], off offset:1536
	v_pk_mul_f32 v[8:9], v[158:159], v[70:71]
	v_pk_mul_f32 v[30:31], v[160:161], v[66:67]
	v_pk_add_f32 v[32:33], v[176:177], 1.0 op_sel_hi:[1,0]
	v_pk_add_f32 v[34:35], v[174:175], 1.0 op_sel_hi:[1,0]
	v_pk_fma_f32 v[30:31], v[32:33], v[30:31], v[192:193]
	v_pk_fma_f32 v[8:9], v[34:35], v[8:9], v[190:191]
	v_bfe_u32 v33, v30, 16, 1
	v_bfe_u32 v7, v8, 16, 1
	v_bfe_u32 v32, v9, 16, 1
	v_bfe_u32 v34, v31, 16, 1
	v_add3_u32 v7, v8, v7, s26
	v_add3_u32 v8, v9, v32, s26
	v_add3_u32 v9, v30, v33, s26
	v_add3_u32 v30, v31, v34, s26
	v_lshrrev_b32_e32 v7, 16, v7
	v_lshrrev_b32_e32 v9, 16, v9
	v_and_or_b32 v8, v8, s27, v7
	v_and_or_b32 v9, v30, s27, v9
	global_store_dwordx2 v[78:79], v[8:9], off
	v_pk_mul_f32 v[8:9], v[162:163], v[96:97]
	v_pk_mul_f32 v[30:31], v[164:165], v[72:73]
	v_pk_add_f32 v[32:33], v[180:181], 1.0 op_sel_hi:[1,0]
	v_pk_add_f32 v[34:35], v[178:179], 1.0 op_sel_hi:[1,0]
	v_pk_fma_f32 v[30:31], v[32:33], v[30:31], v[196:197]
	v_pk_fma_f32 v[8:9], v[34:35], v[8:9], v[194:195]
	v_bfe_u32 v33, v30, 16, 1
	v_bfe_u32 v7, v8, 16, 1
	v_bfe_u32 v32, v9, 16, 1
	v_bfe_u32 v34, v31, 16, 1
	v_add3_u32 v7, v8, v7, s26
	v_add3_u32 v8, v9, v32, s26
	v_add3_u32 v9, v30, v33, s26
	v_add3_u32 v30, v31, v34, s26
	v_lshrrev_b32_e32 v7, 16, v7
	v_lshrrev_b32_e32 v9, 16, v9
	v_and_or_b32 v8, v8, s27, v7
	v_and_or_b32 v9, v30, s27, v9
	global_store_dwordx2 v[78:79], v[8:9], off offset:512
	ds_bpermute_b32 v7, v87, v103
	s_waitcnt lgkmcnt(0)
	v_add_f32_e32 v7, v103, v7
	v_pk_mul_f32 v[8:9], v[28:29], v[6:7] op_sel_hi:[1,0]
	v_pk_mul_f32 v[26:27], v[26:27], v[6:7] op_sel_hi:[1,0]
	v_pk_mul_f32 v[8:9], v[168:169], v[8:9]
	v_pk_mul_f32 v[26:27], v[166:167], v[26:27]
	v_pk_add_f32 v[28:29], v[184:185], 1.0 op_sel_hi:[1,0]
	v_pk_add_f32 v[30:31], v[182:183], 1.0 op_sel_hi:[1,0]
	v_pk_fma_f32 v[8:9], v[8:9], v[28:29], v[208:209]
	v_pk_fma_f32 v[26:27], v[26:27], v[30:31], v[206:207]
	v_bfe_u32 v30, v8, 16, 1
	v_bfe_u32 v28, v26, 16, 1
	v_bfe_u32 v29, v27, 16, 1
	v_bfe_u32 v31, v9, 16, 1
	v_add3_u32 v26, v26, v28, s26
	v_add3_u32 v8, v8, v30, s26
	v_add3_u32 v27, v27, v29, s26
	v_add3_u32 v9, v9, v31, s26
	v_lshrrev_b32_e32 v26, 16, v26
	v_lshrrev_b32_e32 v28, 16, v8
	v_and_or_b32 v8, v27, s27, v26
	v_and_or_b32 v9, v9, s27, v28
	global_store_dwordx2 v[78:79], v[8:9], off offset:1024
	ds_bpermute_b32 v8, v88, v7
	s_waitcnt lgkmcnt(0)
	v_add_f32_e32 v7, v7, v8
	ds_bpermute_b32 v8, v89, v7
	s_waitcnt lgkmcnt(0)
	v_add_f32_e32 v7, v7, v8
	v_fmamk_f32 v7, v7, 0x3a800000, v90
	v_cmp_gt_f32_e32 vcc, s3, v7
	v_mul_f32_e32 v8, 0x4f800000, v7
	s_nop 0
	v_cndmask_b32_e32 v38, v7, v8, vcc
	v_pk_mul_f32 v[8:9], v[24:25], v[6:7] op_sel_hi:[1,0]
	v_pk_mul_f32 v[6:7], v[22:23], v[6:7] op_sel_hi:[1,0]
	v_sqrt_f32_e32 v39, v38
	v_cmp_class_f32_e64 s[0:1], v38, v91
	v_pk_mul_f32 v[6:7], v[6:7], v[170:171]
	v_pk_mul_f32 v[8:9], v[8:9], v[172:173]
	v_pk_add_f32 v[22:23], v[188:189], 1.0 op_sel_hi:[1,0]
	v_pk_add_f32 v[24:25], v[186:187], 1.0 op_sel_hi:[1,0]
	v_pk_fma_f32 v[8:9], v[8:9], v[22:23], v[212:213]
	v_pk_fma_f32 v[6:7], v[6:7], v[24:25], v[210:211]
	v_bfe_u32 v24, v8, 16, 1
	v_bfe_u32 v22, v6, 16, 1
	v_bfe_u32 v23, v7, 16, 1
	v_bfe_u32 v25, v9, 16, 1
	v_add3_u32 v6, v6, v22, s26
	v_add3_u32 v8, v8, v24, s26
	v_add3_u32 v7, v7, v23, s26
	v_add3_u32 v9, v9, v25, s26
	v_lshrrev_b32_e32 v6, 16, v6
	v_lshrrev_b32_e32 v8, 16, v8
	v_and_or_b32 v6, v7, s27, v6
	v_and_or_b32 v7, v9, s27, v8
	global_store_dwordx2 v[78:79], v[6:7], off offset:1536
	v_add_u32_e32 v6, -1, v39
	v_add_u32_e32 v7, 1, v39
	v_fma_f32 v8, -v6, v39, v38
	v_fma_f32 v9, -v7, v39, v38
	v_cmp_ge_f32_e64 s[4:5], 0, v8
	v_cmp_lt_f32_e64 s[6:7], 0, v9
	s_nop 0
	v_cndmask_b32_e64 v6, v39, v6, s[4:5]
	v_cndmask_b32_e64 v6, v6, v7, s[6:7]
	v_mul_f32_e32 v7, 0x37800000, v6
	v_cndmask_b32_e32 v6, v6, v7, vcc
	v_cndmask_b32_e64 v6, v6, v38, s[0:1]
	v_div_scale_f32 v7, s[0:1], v6, v6, 1.0
	v_rcp_f32_e32 v9, v7
	v_div_scale_f32 v8, vcc, 1.0, v6, 1.0
	s_add_i32 s0, s38, 0x2000
	v_fma_f32 v34, -v7, v9, 1.0
	v_fmac_f32_e32 v9, v34, v9
	v_mul_f32_e32 v34, v8, v9
	v_fma_f32 v35, -v7, v34, v8
	v_fmac_f32_e32 v34, v35, v9
	v_fma_f32 v7, -v7, v34, v8
	v_div_fmas_f32 v7, v7, v9, v34
	v_div_fixup_f32 v6, v7, v6, 1.0
	v_pk_mul_f32 v[8:9], v[20:21], v[6:7] op_sel_hi:[1,0]
	v_pk_mul_f32 v[18:19], v[18:19], v[6:7] op_sel_hi:[1,0]
	s_cmpk_lt_i32 s38, 0x2000
	s_mov_b32 s38, s0
	v_pk_mul_f32 v[18:19], v[158:159], v[18:19]
	v_pk_mul_f32 v[8:9], v[160:161], v[8:9]
	v_pk_add_f32 v[20:21], v[176:177], 1.0 op_sel_hi:[1,0]
	v_pk_add_f32 v[22:23], v[174:175], 1.0 op_sel_hi:[1,0]
	v_pk_fma_f32 v[8:9], v[20:21], v[8:9], v[192:193]
	v_pk_fma_f32 v[18:19], v[22:23], v[18:19], v[190:191]
	v_bfe_u32 v21, v8, 16, 1
	v_bfe_u32 v7, v18, 16, 1
	v_bfe_u32 v20, v19, 16, 1
	v_bfe_u32 v22, v9, 16, 1
	v_add3_u32 v7, v18, v7, s26
	v_add3_u32 v8, v8, v21, s26
	v_add3_u32 v18, v19, v20, s26
	v_add3_u32 v9, v9, v22, s26
	v_lshrrev_b32_e32 v7, 16, v7
	v_lshrrev_b32_e32 v19, 16, v8
	v_and_or_b32 v8, v18, s27, v7
	v_and_or_b32 v9, v9, s27, v19
	global_store_dwordx2 v[76:77], v[8:9], off
	v_pk_mul_f32 v[8:9], v[16:17], v[6:7] op_sel_hi:[1,0]
	v_pk_mul_f32 v[14:15], v[14:15], v[6:7] op_sel_hi:[1,0]
	v_pk_mul_f32 v[8:9], v[164:165], v[8:9]
	v_pk_mul_f32 v[14:15], v[162:163], v[14:15]
	v_pk_add_f32 v[16:17], v[180:181], 1.0 op_sel_hi:[1,0]
	v_pk_add_f32 v[18:19], v[178:179], 1.0 op_sel_hi:[1,0]
	v_pk_fma_f32 v[8:9], v[16:17], v[8:9], v[196:197]
	v_pk_fma_f32 v[14:15], v[18:19], v[14:15], v[194:195]
	v_bfe_u32 v17, v8, 16, 1
	v_bfe_u32 v7, v14, 16, 1
	v_bfe_u32 v16, v15, 16, 1
	v_bfe_u32 v18, v9, 16, 1
	v_add3_u32 v7, v14, v7, s26
	v_add3_u32 v8, v8, v17, s26
	v_add3_u32 v14, v15, v16, s26
	v_add3_u32 v9, v9, v18, s26
	v_lshrrev_b32_e32 v7, 16, v7
	v_lshrrev_b32_e32 v15, 16, v8
	v_and_or_b32 v8, v14, s27, v7
	v_and_or_b32 v9, v9, s27, v15
	global_store_dwordx2 v[76:77], v[8:9], off offset:512
	v_pk_mul_f32 v[8:9], v[12:13], v[6:7] op_sel_hi:[1,0]
	v_pk_mul_f32 v[10:11], v[10:11], v[6:7] op_sel_hi:[1,0]
	v_pk_mul_f32 v[8:9], v[168:169], v[8:9]
	v_pk_mul_f32 v[10:11], v[166:167], v[10:11]
	v_pk_add_f32 v[12:13], v[184:185], 1.0 op_sel_hi:[1,0]
	v_pk_add_f32 v[14:15], v[182:183], 1.0 op_sel_hi:[1,0]
	v_pk_fma_f32 v[8:9], v[8:9], v[12:13], v[208:209]
	v_pk_fma_f32 v[10:11], v[10:11], v[14:15], v[206:207]
	v_bfe_u32 v13, v8, 16, 1
	v_bfe_u32 v7, v10, 16, 1
	v_bfe_u32 v12, v11, 16, 1
	v_bfe_u32 v14, v9, 16, 1
	v_add3_u32 v7, v10, v7, s26
	v_add3_u32 v8, v8, v13, s26
	v_add3_u32 v10, v11, v12, s26
	v_add3_u32 v9, v9, v14, s26
	v_lshrrev_b32_e32 v7, 16, v7
	v_lshrrev_b32_e32 v11, 16, v8
	v_and_or_b32 v8, v10, s27, v7
	v_and_or_b32 v9, v9, s27, v11
	global_store_dwordx2 v[76:77], v[8:9], off offset:1024
	s_nop 0
	v_pk_mul_f32 v[4:5], v[4:5], v[6:7] op_sel_hi:[1,0]
	v_pk_mul_f32 v[2:3], v[2:3], v[6:7] op_sel_hi:[1,0]
	v_pk_mul_f32 v[4:5], v[4:5], v[172:173]
	v_pk_mul_f32 v[2:3], v[2:3], v[170:171]
	v_pk_add_f32 v[6:7], v[188:189], 1.0 op_sel_hi:[1,0]
	v_pk_add_f32 v[8:9], v[186:187], 1.0 op_sel_hi:[1,0]
	v_pk_fma_f32 v[4:5], v[4:5], v[6:7], v[212:213]
	v_pk_fma_f32 v[2:3], v[2:3], v[8:9], v[210:211]
	v_bfe_u32 v8, v4, 16, 1
	v_bfe_u32 v6, v2, 16, 1
	v_bfe_u32 v7, v3, 16, 1
	v_bfe_u32 v9, v5, 16, 1
	v_add3_u32 v2, v2, v6, s26
	v_add3_u32 v4, v4, v8, s26
	v_add3_u32 v3, v3, v7, s26
	v_add3_u32 v5, v5, v9, s26
	v_lshrrev_b32_e32 v2, 16, v2
	v_lshrrev_b32_e32 v4, 16, v4
	v_and_or_b32 v2, v3, s27, v2
	v_and_or_b32 v3, v5, s27, v4
	global_store_dwordx2 v[76:77], v[2:3], off offset:1536
	s_cbranch_scc1 .LBB0_138
	v_readlane_b32 s16, v251, 9
	v_readlane_b32 s17, v251, 10
	v_readlane_b32 s18, v251, 11
	v_readlane_b32 s19, v251, 12
	v_readlane_b32 s20, v251, 13
	v_readlane_b32 s21, v251, 14
	v_readlane_b32 s22, v251, 15
	v_readlane_b32 s23, v251, 16
	v_readlane_b32 s24, v251, 17
	v_readlane_b32 s25, v251, 18
	v_readlane_b32 s26, v251, 19
	v_readlane_b32 s27, v251, 20
	v_readlane_b32 s28, v251, 21
	v_readlane_b32 s29, v251, 22
	v_readlane_b32 s30, v251, 23
	v_readlane_b32 s31, v251, 24
	v_readlane_b32 s16, v251, 25
	v_readlane_b32 s17, v251, 26
	v_readlane_b32 s18, v251, 27
	v_readlane_b32 s19, v251, 28
	v_readlane_b32 s20, v251, 29
	v_readlane_b32 s21, v251, 30
	v_readlane_b32 s22, v251, 31
	v_readlane_b32 s23, v251, 32
	v_readlane_b32 s24, v251, 33
	v_readlane_b32 s25, v251, 34
	v_readlane_b32 s26, v251, 35
	v_readlane_b32 s27, v251, 36
	v_readlane_b32 s28, v251, 37
	v_readlane_b32 s29, v251, 38
	v_readlane_b32 s30, v251, 39
	v_readlane_b32 s31, v251, 40
